# latent Hyena K loop: odd-tile A fragments derived from even-tile fragments with v_permlane32_swap + v_cndmask instead of 4 more global loads per iteration
# baseline (speedup 1.0000x reference)
; DI void hyena_item_lat(const Params& p, int l, int it) {
;     ...
;   const int c = it >> 2, f = l, L = 2048, posoff = CTXL;
;   const int tt0 = (it & 3) * 512 + w * 128;
;   const u16* R0 = WSP(const u16, OFF_RF) + ((size_t)(f * 256 + c) * 2) * RSTR;
;   const u16* R1 = R0 + RSTR;
;   const u16* UT = WSP(const u16, OFF_UT);
;   const int l16 = lane & 15, kg = lane >> 4;
;   f32x4 acc[8];
; #pragma unroll
;   for (int i = 0; i < 8; ++i) acc[i] = (f32x4){0.f, 0.f, 0.f, 0.f};
;   const u16* ub = UT + ((size_t)(c * 16 + l16)) * TPB + posoff + kg * 8;
;   const u16* rsel = (l16 & 1) ? (R1 - 1) : R0;
;   const int nb = L - (tt0 + l16) + kg * 8;
;   union AF { u32 u[4]; bf16x8 v; };
;   AF a[8];
;     ...
; #pragma unroll
;   for (int i = 2; i < 8; ++i) HY_LOADA(a[i], nb - 16 * i)
; #pragma unroll 1
;   for (int sb = 0; sb < L; sb += 128) {
; #pragma unroll
;     for (int u = 0; u < 4; ++u) {
;       const int s0 = sb + 32 * u;
;       HY_LOADA(a[(0 - 2 * u) & 7], nb + s0)
;       HY_LOADA(a[(1 - 2 * u) & 7], nb - 16 + s0)
;       const bf16x8 bfrag = *(const bf16x8*)(ub + s0);
; #pragma unroll
;       for (int i = 0; i < 8; ++i) acc[i] = __builtin_amdgcn_mfma_f32_16x16x32_bf16(a[(i - 2 * u) & 7].v, bfrag, acc[i], 0, 0, 0);
;     }
;   }
.LBB0_1137:
	s_andn2_b64 vcc, exec, s[34:35]
	s_cbranch_vccnz .LBB0_1141
	s_ashr_i32 s34, s13, 2
	v_mov_b32_e32 v0, v218
	v_mov_b32_e32 v1, v218
	s_add_i32 s36, s34, s42
	s_lshl_b32 s13, s13, 9
	s_ashr_i32 s37, s36, 31
	s_mul_i32 s38, s36, 0x4040
	v_readlane_b32 s16, v254, 47
	v_lshlrev_b32_e32 v1, 1, v1
	s_mul_hi_i32 s35, s36, 0x4040
	v_readlane_b32 s17, v254, 48
	s_add_u32 s38, s16, s38
	v_and_b32_e32 v1, 0xffffff80, v1
	s_addc_u32 s39, s17, s35
	s_and_b32 s13, s13, 0x600
	v_add_u32_e32 v63, s13, v1
	v_and_b32_e32 v62, 15, v0
	v_bfe_u32 v64, v0, 4, 2
	v_bfe_i32 v0, v0, 0, 1
	v_lshlrev_b32_e32 v1, 3, v64
	v_and_b32_e32 v172, 0x201e, v0
	v_or_b32_e32 v0, v63, v62
	v_sub_u32_e32 v58, v1, v0
	v_lshl_add_u64 v[56:57], s[38:39], 0, v[172:173]
	v_ashrrev_i32_e32 v59, 31, v58
	v_lshl_add_u64 v[0:1], v[58:59], 1, v[56:57]
	global_load_dwordx4 v[40:43], v[0:1], off offset:4032
	global_load_dwordx4 v[44:47], v[0:1], off offset:4000
	global_load_dwordx4 v[32:35], v[0:1], off offset:3968
	global_load_dwordx4 v[36:39], v[0:1], off offset:3936
	global_load_dwordx4 v[48:51], v[0:1], off offset:3904
	global_load_dwordx4 v[52:55], v[0:1], off offset:3872
	s_lshl_b32 s35, s34, 4
	v_or_b32_e32 v59, s35, v62
	v_mad_i64_i32 v[0:1], s[38:39], v59, s9, 0
	v_readlane_b32 s16, v255, 56
	v_lshl_or_b32 v0, v64, 4, v0
	v_readlane_b32 s17, v255, 57
	v_mov_b32_e32 v28, 0
	s_mov_b64 s[46:47], s[20:21]
	s_movk_i32 s13, 0xff80
	v_lshl_add_u64 v[60:61], s[16:17], 0, v[0:1]
	v_mov_b32_e32 v29, v28
	v_mov_b32_e32 v30, v28
	v_mov_b32_e32 v31, v28
	v_mov_b32_e32 v24, v28
	v_mov_b32_e32 v25, v28
	v_mov_b32_e32 v26, v28
	v_mov_b32_e32 v27, v28
	v_mov_b32_e32 v20, v28
	v_mov_b32_e32 v21, v28
	v_mov_b32_e32 v22, v28
	v_mov_b32_e32 v23, v28
	v_mov_b32_e32 v16, v28
	v_mov_b32_e32 v17, v28
	v_mov_b32_e32 v18, v28
	v_mov_b32_e32 v19, v28
	v_mov_b32_e32 v12, v28
	v_mov_b32_e32 v13, v28
	v_mov_b32_e32 v14, v28
	v_mov_b32_e32 v15, v28
	v_mov_b32_e32 v8, v28
	v_mov_b32_e32 v9, v28
	v_mov_b32_e32 v10, v28
	v_mov_b32_e32 v11, v28
	v_mov_b32_e32 v4, v28
	v_mov_b32_e32 v5, v28
	v_mov_b32_e32 v6, v28
	v_mov_b32_e32 v7, v28
	v_mov_b32_e32 v0, v28
	v_mov_b32_e32 v1, v28
	v_mov_b32_e32 v2, v28
	v_mov_b32_e32 v3, v28
	v_and_b32_e32 v92, 0xc0, v218
	v_mov_b32_e32 v93, 0
	v_lshlrev_b32_e32 v94, 4, v218
	v_and_b32_e32 v95, 63, v218
	v_lshl_add_u64 v[90:91], v[92:93], 0, v[60:61]
	v_lshlrev_b32_e32 v95, 4, v95
	global_load_dwordx4 v[82:85], v[90:91], off offset:-192
	s_mov_b32 vcc_lo, 0
	s_mov_b32 vcc_hi, -1
.LBB0_1139:
	s_waitcnt vmcnt(0)
	ds_write_b128 v94, v[82:85]
	s_waitcnt lgkmcnt(0)
	s_barrier
	ds_read_b128 v[66:69], v95
	ds_read_b128 v[70:73], v95 offset:1024
	ds_read_b128 v[86:89], v95 offset:2048
	ds_read_b128 v[74:77], v95 offset:3072
	v_xor_b32_e32 v94, 0x1000, v94
	v_xor_b32_e32 v95, 0x1000, v95
	s_mov_b64 s[38:39], 0x100
	s_waitcnt lgkmcnt(0)
	v_mfma_f32_16x16x32_bf16 v[4:7], v[48:51], v[66:69], v[4:7]
	v_add_u32_e32 v49, s13, v58
	v_add_u32_e32 v48, 0x880, v49
	v_mfma_f32_16x16x32_bf16 v[0:3], v[52:55], v[66:69], v[0:3]
	v_ashrrev_i32_e32 v49, 31, v48
	v_lshl_add_u64 v[78:79], v[48:49], 1, v[56:57]
	v_mfma_f32_16x16x32_bf16 v[12:15], v[32:35], v[66:69], v[12:15]
	global_load_dwordx4 v[48:51], v[78:79], off offset:64
	s_addk_i32 s13, 0x80
	v_mfma_f32_16x16x32_bf16 v[8:11], v[36:39], v[66:69], v[8:11]
	s_cmpk_lt_u32 s13, 0x780
	v_mfma_f32_16x16x32_bf16 v[4:7], v[32:35], v[70:73], v[4:7]
	global_load_dwordx4 v[32:35], v[78:79], off
	v_mfma_f32_16x16x32_bf16 v[0:3], v[36:39], v[70:73], v[0:3]
	v_mfma_f32_16x16x32_bf16 v[20:23], v[40:43], v[66:69], v[20:23]
	v_mfma_f32_16x16x32_bf16 v[16:19], v[44:47], v[66:69], v[16:19]
	v_mfma_f32_16x16x32_bf16 v[12:15], v[40:43], v[70:73], v[12:15]
	v_mfma_f32_16x16x32_bf16 v[8:11], v[44:47], v[70:73], v[8:11]
	s_waitcnt vmcnt(0)
	v_mov_b64_e32 v[104:105], v[40:41]
	v_mov_b64_e32 v[106:107], v[42:43]
	v_mov_b64_e32 v[108:109], v[32:33]
	v_mov_b64_e32 v[110:111], v[34:35]
	s_nop 1
	v_permlane32_swap_b32 v104, v108
	v_permlane32_swap_b32 v105, v109
	v_permlane32_swap_b32 v106, v110
	v_permlane32_swap_b32 v107, v111
	s_nop 1
	v_cndmask_b32_e32 v36, v108, v104, vcc
	v_cndmask_b32_e32 v37, v109, v105, vcc
	v_cndmask_b32_e32 v38, v110, v106, vcc
	v_cndmask_b32_e32 v39, v111, v107, vcc
	v_mfma_f32_16x16x32_bf16 v[28:31], v[32:35], v[66:69], v[28:31]
	v_mfma_f32_16x16x32_bf16 v[20:23], v[32:35], v[70:73], v[20:23]
	v_mov_b64_e32 v[104:105], v[32:33]
	v_mov_b64_e32 v[106:107], v[34:35]
	v_mov_b64_e32 v[108:109], v[48:49]
	v_mov_b64_e32 v[110:111], v[50:51]
	s_nop 1
	v_permlane32_swap_b32 v104, v108
	v_permlane32_swap_b32 v105, v109
	v_permlane32_swap_b32 v106, v110
	v_permlane32_swap_b32 v107, v111
	s_nop 1
	v_cndmask_b32_e32 v52, v108, v104, vcc
	v_cndmask_b32_e32 v53, v109, v105, vcc
	v_cndmask_b32_e32 v54, v110, v106, vcc
	v_cndmask_b32_e32 v55, v111, v107, vcc
	global_load_dwordx4 v[82:85], v[90:91], off offset:64
	v_lshl_add_u64 v[90:91], v[90:91], 0, s[38:39]
	v_lshl_add_u64 v[60:61], v[60:61], 0, s[38:39]
	v_mfma_f32_16x16x32_bf16 v[28:31], v[48:51], v[70:73], v[28:31]
	v_mfma_f32_16x16x32_bf16 v[24:27], v[36:39], v[66:69], v[24:27]
	v_mfma_f32_16x16x32_bf16 v[16:19], v[36:39], v[70:73], v[16:19]
	v_mfma_f32_16x16x32_bf16 v[24:27], v[52:55], v[70:73], v[24:27]
	v_mfma_f32_16x16x32_bf16 v[4:7], v[40:43], v[86:89], v[4:7]
	v_mfma_f32_16x16x32_bf16 v[0:3], v[44:47], v[86:89], v[0:3]
	global_load_dwordx4 v[40:43], v[78:79], off offset:192
	v_mfma_f32_16x16x32_bf16 v[12:15], v[32:35], v[86:89], v[12:15]
	v_mfma_f32_16x16x32_bf16 v[8:11], v[36:39], v[86:89], v[8:11]
	v_mfma_f32_16x16x32_bf16 v[4:7], v[32:35], v[74:77], v[4:7]
	v_mfma_f32_16x16x32_bf16 v[0:3], v[36:39], v[74:77], v[0:3]
	global_load_dwordx4 v[32:35], v[78:79], off offset:128
	v_mfma_f32_16x16x32_bf16 v[20:23], v[48:51], v[86:89], v[20:23]
	v_mfma_f32_16x16x32_bf16 v[16:19], v[52:55], v[86:89], v[16:19]
	v_mfma_f32_16x16x32_bf16 v[12:15], v[48:51], v[74:77], v[12:15]
	v_mfma_f32_16x16x32_bf16 v[8:11], v[52:55], v[74:77], v[8:11]
	s_waitcnt vmcnt(0)
; DI float bf2f(u16 v) { return __uint_as_float(((u32)v) << 16); }
; DI void hyena_item_lat(const Params& p, int l, int it) {
;     ...
;   for (int sb = 0; sb < L; sb += 128) {
; #pragma unroll
;     for (int u = 0; u < 4; ++u) {
;       const int s0 = sb + 32 * u;
;       HY_LOADA(a[(0 - 2 * u) & 7], nb + s0)
;       HY_LOADA(a[(1 - 2 * u) & 7], nb - 16 + s0)
;       const bf16x8 bfrag = *(const bf16x8*)(ub + s0);
; #pragma unroll
;       for (int i = 0; i < 8; ++i) acc[i] = __builtin_amdgcn_mfma_f32_16x16x32_bf16(a[(i - 2 * u) & 7].v, bfrag, acc[i], 0, 0, 0);
;     }
;   }
;     ...
;   float ssq = 0.f;
;   for (int t = 0; t < 32; ++t) ssq += WSP(const float, OFF_PART)[(size_t)(f * 32 + t) * 256 + c];
;   const float scale = rsqrtf(ssq + EPSF);
;   const float bias = p.in[I_HYBIAS][l * 256 + c];
;   const u16* X1C = WSP(const u16, OFF_X1C);
;   u16* YM = WSP(u16, OFF_ACT);
;   const int b = l16;
; #pragma unroll
;   for (int i = 0; i < 8; ++i)
; #pragma unroll
;     for (int r = 0; r < 4; ++r) {
;       const int t = tt0 + 16 * i + kg * 4 + r;
;       const size_t row = (size_t)b * TPB + posoff + t;
;       const float uu = bf2f(UT[((size_t)(c * 16 + b)) * TPB + posoff + t]);
	v_mov_b64_e32 v[104:105], v[48:49]
	v_mov_b64_e32 v[106:107], v[50:51]
	v_mov_b64_e32 v[108:109], v[32:33]
	v_mov_b64_e32 v[110:111], v[34:35]
	s_nop 1
	v_permlane32_swap_b32 v104, v108
	v_permlane32_swap_b32 v105, v109
	v_permlane32_swap_b32 v106, v110
	v_permlane32_swap_b32 v107, v111
	s_nop 1
	v_cndmask_b32_e32 v36, v108, v104, vcc
	v_cndmask_b32_e32 v37, v109, v105, vcc
	v_cndmask_b32_e32 v38, v110, v106, vcc
	v_cndmask_b32_e32 v39, v111, v107, vcc
	v_mfma_f32_16x16x32_bf16 v[28:31], v[32:35], v[86:89], v[28:31]
	v_mfma_f32_16x16x32_bf16 v[20:23], v[32:35], v[74:77], v[20:23]
	v_mov_b64_e32 v[104:105], v[32:33]
	v_mov_b64_e32 v[106:107], v[34:35]
	v_mov_b64_e32 v[108:109], v[40:41]
	v_mov_b64_e32 v[110:111], v[42:43]
	s_nop 1
	v_permlane32_swap_b32 v104, v108
	v_permlane32_swap_b32 v105, v109
	v_permlane32_swap_b32 v106, v110
	v_permlane32_swap_b32 v107, v111
	s_nop 1
	v_cndmask_b32_e32 v44, v108, v104, vcc
	v_cndmask_b32_e32 v45, v109, v105, vcc
	v_cndmask_b32_e32 v46, v110, v106, vcc
	v_cndmask_b32_e32 v47, v111, v107, vcc
	v_mfma_f32_16x16x32_bf16 v[28:31], v[40:43], v[74:77], v[28:31]
	v_mfma_f32_16x16x32_bf16 v[24:27], v[36:39], v[86:89], v[24:27]
	v_mfma_f32_16x16x32_bf16 v[16:19], v[36:39], v[74:77], v[16:19]
	v_mfma_f32_16x16x32_bf16 v[24:27], v[44:47], v[74:77], v[24:27]
	s_cbranch_scc1 .LBB0_1139
	s_waitcnt vmcnt(0)
	v_mov_b64_e32 v[32:33], s[96:97]
	v_mad_i64_i32 v[32:33], s[38:39], v59, s9, v[32:33]
	s_mov_b64 s[38:39], 0x15600200
	s_ashr_i32 s35, s34, 31
	v_lshl_add_u64 v[32:33], v[32:33], 0, s[38:39]
	s_lshl_b64 s[38:39], s[34:35], 2
	s_add_u32 s38, s43, s38
	s_addc_u32 s39, s44, s39
	global_load_dword v38, v173, s[38:39]
	global_load_dword v39, v173, s[38:39] offset:1024
	global_load_dword v40, v173, s[38:39] offset:2048
	global_load_dword v41, v173, s[38:39] offset:3072
	v_mov_b32_e32 v92, 0x1000
	global_load_dword v42, v92, s[38:39]
	global_load_dword v43, v92, s[38:39] offset:1024
	global_load_dword v44, v92, s[38:39] offset:2048
	global_load_dword v45, v92, s[38:39] offset:3072
	v_mov_b32_e32 v92, 0x2000
	global_load_dword v46, v92, s[38:39]
	global_load_dword v47, v92, s[38:39] offset:1024
	global_load_dword v48, v92, s[38:39] offset:2048
	global_load_dword v49, v92, s[38:39] offset:3072
	v_mov_b32_e32 v92, 0x3000
	global_load_dword v50, v92, s[38:39]
	global_load_dword v51, v92, s[38:39] offset:1024
	global_load_dword v52, v92, s[38:39] offset:2048
	global_load_dword v53, v92, s[38:39] offset:3072
	v_mov_b32_e32 v92, 0x4000
	global_load_dword v54, v92, s[38:39]
	global_load_dword v55, v92, s[38:39] offset:1024
	global_load_dword v56, v92, s[38:39] offset:2048
	global_load_dword v57, v92, s[38:39] offset:3072
	v_mov_b32_e32 v92, 0x5000
	global_load_dword v58, v92, s[38:39]
	global_load_dword v65, v92, s[38:39] offset:1024
	global_load_dword v66, v92, s[38:39] offset:2048
	global_load_dword v67, v92, s[38:39] offset:3072
	v_mov_b32_e32 v92, 0x6000
	global_load_dword v68, v92, s[38:39]
	global_load_dword v69, v92, s[38:39] offset:1024
	global_load_dword v70, v92, s[38:39] offset:2048
	global_load_dword v71, v92, s[38:39] offset:3072
	v_mov_b32_e32 v92, 0x7000
	global_load_dword v72, v92, s[38:39]
	global_load_dword v73, v92, s[38:39] offset:1024
	global_load_dword v74, v92, s[38:39] offset:2048
	global_load_dword v75, v92, s[38:39] offset:3072
	v_readlane_b32 s16, v254, 29
	s_lshl_b64 s[36:37], s[36:37], 2
	v_readlane_b32 s18, v254, 31
	v_readlane_b32 s19, v254, 32
	s_add_u32 s36, s18, s36
	s_addc_u32 s37, s19, s37
	global_load_dword v37, v173, s[36:37]
	s_movk_i32 s13, 0x900
	v_lshl_or_b32 v34, v64, 2, v63
	v_mov_b32_e32 v35, 0x100
	v_mad_u32_u24 v172, v62, s13, v35
	v_mov_b32_e32 v35, 0
	v_lshl_add_u64 v[94:95], v[34:35], 1, v[32:33]
	global_load_dwordx2 v[76:77], v[94:95], off
	global_load_dwordx2 v[78:79], v[94:95], off offset:32
	global_load_dwordx2 v[80:81], v[94:95], off offset:64
	global_load_dwordx2 v[82:83], v[94:95], off offset:96
	global_load_dwordx2 v[84:85], v[94:95], off offset:128
	global_load_dwordx2 v[86:87], v[94:95], off offset:160
	global_load_dwordx2 v[88:89], v[94:95], off offset:192
	global_load_dwordx2 v[90:91], v[94:95], off offset:224
	v_readlane_b32 s17, v254, 30
	s_lshl_b64 s[34:35], s[34:35], 1
	v_readlane_b32 s16, v255, 42
	v_readlane_b32 s17, v255, 43
	v_readlane_b32 s20, v254, 33
	v_readlane_b32 s21, v254, 34
	v_readlane_b32 s24, v254, 37
	v_readlane_b32 s18, v254, 10
	s_mov_b64 s[20:21], s[46:47]
	s_mov_b32 s24, s64
	v_readlane_b32 s22, v254, 35
	v_readlane_b32 s23, v254, 36
	v_readlane_b32 s25, v254, 38
	v_readlane_b32 s26, v254, 39
	v_readlane_b32 s27, v254, 40
	v_readlane_b32 s28, v254, 41
	v_readlane_b32 s29, v254, 42
	v_readlane_b32 s30, v254, 43
	v_readlane_b32 s31, v254, 44
	v_readlane_b32 s19, v254, 11
	s_add_u32 s38, s16, s34
	s_addc_u32 s39, s17, s35
	s_add_u32 s36, s6, s34
	s_addc_u32 s37, s7, s35
	v_lshlrev_b32_e32 v142, 13, v62
	v_lshl_add_u32 v142, v34, 2, v142
	s_waitcnt vmcnt(0)
; DI u16 f2bf(float x) { u32 u = __float_as_uint(x); u += 0x7fffu + ((u >> 16) & 1u); return (u16)(u >> 16); }
; DI float bf2f(u16 v) { return __uint_as_float(((u32)v) << 16); }
; DI void hyena_item_lat(const Params& p, int l, int it) {
;     ...
;   float ssq = 0.f;
;   for (int t = 0; t < 32; ++t) ssq += WSP(const float, OFF_PART)[(size_t)(f * 32 + t) * 256 + c];
;   const float scale = rsqrtf(ssq + EPSF);
;   const float bias = p.in[I_HYBIAS][l * 256 + c];
;   const u16* X1C = WSP(const u16, OFF_X1C);
;   u16* YM = WSP(u16, OFF_ACT);
;   const int b = l16;
; #pragma unroll
;   for (int i = 0; i < 8; ++i)
; #pragma unroll
;     for (int r = 0; r < 4; ++r) {
;       const int t = tt0 + 16 * i + kg * 4 + r;
;       const size_t row = (size_t)b * TPB + posoff + t;
;       const float uu = bf2f(UT[((size_t)(c * 16 + b)) * TPB + posoff + t]);
;       const float x1 = bf2f(X1C[row * 256 + c]);
;       YM[row * 1024 + c] = f2bf(x1 * (scale * acc[i][r] + bias * uu));
;     }
	v_add_f32_e32 v36, 0, v38
	v_add_f32_e32 v36, v36, v39
	v_add_f32_e32 v36, v36, v40
	v_add_f32_e32 v36, v36, v41
	v_add_f32_e32 v36, v36, v42
	v_add_f32_e32 v36, v36, v43
	v_add_f32_e32 v36, v36, v44
	v_add_f32_e32 v36, v36, v45
	v_add_f32_e32 v36, v36, v46
	v_add_f32_e32 v36, v36, v47
	v_add_f32_e32 v36, v36, v48
	v_add_f32_e32 v36, v36, v49
	v_add_f32_e32 v36, v36, v50
	v_add_f32_e32 v36, v36, v51
	v_add_f32_e32 v36, v36, v52
	v_add_f32_e32 v36, v36, v53
	v_add_f32_e32 v36, v36, v54
	v_add_f32_e32 v36, v36, v55
	v_add_f32_e32 v36, v36, v56
	v_add_f32_e32 v36, v36, v57
	v_add_f32_e32 v36, v36, v58
	v_add_f32_e32 v36, v36, v65
	v_add_f32_e32 v36, v36, v66
	v_add_f32_e32 v36, v36, v67
	v_add_f32_e32 v36, v36, v68
	v_add_f32_e32 v36, v36, v69
	v_add_f32_e32 v36, v36, v70
	v_add_f32_e32 v36, v36, v71
	v_add_f32_e32 v36, v36, v72
	v_add_f32_e32 v36, v36, v73
	v_add_f32_e32 v36, v36, v74
	v_add_f32_e32 v36, v36, v75
	s_mov_b32 s13, 0x800000
	v_add_f32_e32 v36, 0x358637bd, v36
	v_cmp_gt_f32_e32 vcc, s13, v36
	v_mul_f32_e32 v35, 0x4b800000, v36
	s_movk_i32 s13, 0x900
	s_nop 0
	v_cndmask_b32_e32 v36, v36, v35, vcc
	v_rsq_f32_e32 v36, v36
	s_nop 0
	v_mul_f32_e32 v35, 0x45800000, v36
	v_cndmask_b32_e32 v36, v36, v35, vcc
	v_lshlrev_b32_e32 v92, 16, v76
	v_mul_f32_e32 v92, v37, v92
	v_fmac_f32_e32 v92, v28, v36
	v_mov_b32_e32 v28, v92
	v_and_b32_e32 v92, 0xffff0000, v76
	v_mul_f32_e32 v92, v37, v92
	v_fmac_f32_e32 v92, v29, v36
	v_mov_b32_e32 v29, v92
	v_lshlrev_b32_e32 v92, 16, v77
	v_mul_f32_e32 v92, v37, v92
	v_fmac_f32_e32 v92, v30, v36
	v_mov_b32_e32 v30, v92
	v_and_b32_e32 v92, 0xffff0000, v77
	v_mul_f32_e32 v92, v37, v92
	v_fmac_f32_e32 v92, v31, v36
	v_mov_b32_e32 v31, v92
	v_lshlrev_b32_e32 v92, 16, v78
	v_mul_f32_e32 v92, v37, v92
	v_fmac_f32_e32 v92, v24, v36
	v_mov_b32_e32 v24, v92
	v_and_b32_e32 v92, 0xffff0000, v78
	v_mul_f32_e32 v92, v37, v92
	v_fmac_f32_e32 v92, v25, v36
	v_mov_b32_e32 v25, v92
	v_lshlrev_b32_e32 v92, 16, v79
	v_mul_f32_e32 v92, v37, v92
	v_fmac_f32_e32 v92, v26, v36
	v_mov_b32_e32 v26, v92
	v_and_b32_e32 v92, 0xffff0000, v79
	v_mul_f32_e32 v92, v37, v92
	v_fmac_f32_e32 v92, v27, v36
	v_mov_b32_e32 v27, v92
	v_lshlrev_b32_e32 v92, 16, v80
	v_mul_f32_e32 v92, v37, v92
	v_fmac_f32_e32 v92, v20, v36
	v_mov_b32_e32 v20, v92
	v_and_b32_e32 v92, 0xffff0000, v80
	v_mul_f32_e32 v92, v37, v92
	v_fmac_f32_e32 v92, v21, v36
	v_mov_b32_e32 v21, v92
	v_lshlrev_b32_e32 v92, 16, v81
	v_mul_f32_e32 v92, v37, v92
	v_fmac_f32_e32 v92, v22, v36
	v_mov_b32_e32 v22, v92
	v_and_b32_e32 v92, 0xffff0000, v81
	v_mul_f32_e32 v92, v37, v92
	v_fmac_f32_e32 v92, v23, v36
	v_mov_b32_e32 v23, v92
	v_lshlrev_b32_e32 v92, 16, v82
	v_mul_f32_e32 v92, v37, v92
	v_fmac_f32_e32 v92, v16, v36
	v_mov_b32_e32 v16, v92
	v_and_b32_e32 v92, 0xffff0000, v82
	v_mul_f32_e32 v92, v37, v92
	v_fmac_f32_e32 v92, v17, v36
	v_mov_b32_e32 v17, v92
	v_lshlrev_b32_e32 v92, 16, v83
	v_mul_f32_e32 v92, v37, v92
	v_fmac_f32_e32 v92, v18, v36
	v_mov_b32_e32 v18, v92
	v_and_b32_e32 v92, 0xffff0000, v83
	v_mul_f32_e32 v92, v37, v92
	v_fmac_f32_e32 v92, v19, v36
	v_mov_b32_e32 v19, v92
	v_lshlrev_b32_e32 v92, 16, v84
	v_mul_f32_e32 v92, v37, v92
	v_fmac_f32_e32 v92, v12, v36
	v_mov_b32_e32 v12, v92
	v_and_b32_e32 v92, 0xffff0000, v84
	v_mul_f32_e32 v92, v37, v92
	v_fmac_f32_e32 v92, v13, v36
	v_mov_b32_e32 v13, v92
	v_lshlrev_b32_e32 v92, 16, v85
	v_mul_f32_e32 v92, v37, v92
	v_fmac_f32_e32 v92, v14, v36
	v_mov_b32_e32 v14, v92
	v_and_b32_e32 v92, 0xffff0000, v85
	v_mul_f32_e32 v92, v37, v92
	v_fmac_f32_e32 v92, v15, v36
	v_mov_b32_e32 v15, v92
	v_lshlrev_b32_e32 v92, 16, v86
	v_mul_f32_e32 v92, v37, v92
	v_fmac_f32_e32 v92, v8, v36
	v_mov_b32_e32 v8, v92
	v_and_b32_e32 v92, 0xffff0000, v86
	v_mul_f32_e32 v92, v37, v92
	v_fmac_f32_e32 v92, v9, v36
	v_mov_b32_e32 v9, v92
	v_lshlrev_b32_e32 v92, 16, v87
	v_mul_f32_e32 v92, v37, v92
	v_fmac_f32_e32 v92, v10, v36
	v_mov_b32_e32 v10, v92
	v_and_b32_e32 v92, 0xffff0000, v87
	v_mul_f32_e32 v92, v37, v92
	v_fmac_f32_e32 v92, v11, v36
	v_mov_b32_e32 v11, v92
	v_lshlrev_b32_e32 v92, 16, v88
	v_mul_f32_e32 v92, v37, v92
	v_fmac_f32_e32 v92, v4, v36
	v_mov_b32_e32 v4, v92
	v_and_b32_e32 v92, 0xffff0000, v88
	v_mul_f32_e32 v92, v37, v92
	v_fmac_f32_e32 v92, v5, v36
	v_mov_b32_e32 v5, v92
	v_lshlrev_b32_e32 v92, 16, v89
	v_mul_f32_e32 v92, v37, v92
	v_fmac_f32_e32 v92, v6, v36
	v_mov_b32_e32 v6, v92
	v_and_b32_e32 v92, 0xffff0000, v89
	v_mul_f32_e32 v92, v37, v92
	v_fmac_f32_e32 v92, v7, v36
	v_mov_b32_e32 v7, v92
	v_lshlrev_b32_e32 v92, 16, v90
	v_mul_f32_e32 v92, v37, v92
	v_fmac_f32_e32 v92, v0, v36
	v_mov_b32_e32 v0, v92
	v_and_b32_e32 v92, 0xffff0000, v90
	v_mul_f32_e32 v92, v37, v92
	v_fmac_f32_e32 v92, v1, v36
	v_mov_b32_e32 v1, v92
	v_lshlrev_b32_e32 v92, 16, v91
	v_mul_f32_e32 v92, v37, v92
	v_fmac_f32_e32 v92, v2, v36
	v_mov_b32_e32 v2, v92
	v_and_b32_e32 v92, 0xffff0000, v91
	v_mul_f32_e32 v92, v37, v92
	v_fmac_f32_e32 v92, v3, v36
	v_mov_b32_e32 v3, v92
	s_lshl_b32 s38, s34, 16
	s_add_u32 s38, s96, s38
	s_addc_u32 s39, s97, 0
	global_store_dwordx4 v142, v[28:31], s[38:39]
	global_store_dwordx4 v142, v[24:27], s[38:39] offset:64
	global_store_dwordx4 v142, v[20:23], s[38:39] offset:128
	global_store_dwordx4 v142, v[16:19], s[38:39] offset:192
	global_store_dwordx4 v142, v[12:15], s[38:39] offset:256
	global_store_dwordx4 v142, v[8:11], s[38:39] offset:320
	global_store_dwordx4 v142, v[4:7], s[38:39] offset:384
	global_store_dwordx4 v142, v[0:3], s[38:39] offset:448
